# accumulator zeroing at every GEMM tile start: 127 v_mov_b32 -> 64 v_mov_b64 with inline 0 (8 sites)
# speedup vs baseline: 1.0096x; 1.0007x over previous
.LBB0_537:
	s_ashr_i32 s27, s26, 31
	s_lshl_b64 s[34:35], s[26:27], 19
	s_add_u32 s34, s76, s34
	s_addc_u32 s35, s77, s35
	s_and_b64 s[36:37], s[0:1], exec
	s_cselect_b32 s27, s35, s39
	s_cselect_b32 s50, s34, s38
	s_ashr_i32 s25, s24, 31
	s_lshl_b64 s[36:37], s[24:25], 19
	s_add_u32 s36, s6, s36
	s_addc_u32 s37, s7, s37
	s_and_b64 s[42:43], s[0:1], exec
	s_cselect_b32 s25, s37, s41
	s_cselect_b32 s51, s36, s40
	s_add_u32 s38, s38, 0x40080
	s_addc_u32 s39, s39, 0
	s_add_u32 s52, s40, 0x100
	v_mov_b32_e32 v0, 0
	s_addc_u32 s53, s41, 0
	s_mov_b32 s54, -2
	v_mov_b32_e32 v1, v0
	v_mov_b64_e32 v[2:3], 0
	v_mov_b64_e32 v[4:5], 0
	v_mov_b64_e32 v[6:7], 0
	v_mov_b64_e32 v[16:17], 0
	v_mov_b64_e32 v[18:19], 0
	v_mov_b64_e32 v[20:21], 0
	v_mov_b64_e32 v[22:23], 0
	v_mov_b64_e32 v[32:33], 0
	v_mov_b64_e32 v[34:35], 0
	v_mov_b64_e32 v[36:37], 0
	v_mov_b64_e32 v[38:39], 0
	v_mov_b64_e32 v[48:49], 0
	v_mov_b64_e32 v[50:51], 0
	v_mov_b64_e32 v[52:53], 0
	v_mov_b64_e32 v[54:55], 0
	v_mov_b64_e32 v[8:9], 0
	v_mov_b64_e32 v[10:11], 0
	v_mov_b64_e32 v[12:13], 0
	v_mov_b64_e32 v[14:15], 0
	v_mov_b64_e32 v[24:25], 0
	v_mov_b64_e32 v[26:27], 0
	v_mov_b64_e32 v[28:29], 0
	v_mov_b64_e32 v[30:31], 0
	v_mov_b64_e32 v[40:41], 0
	v_mov_b64_e32 v[42:43], 0
	v_mov_b64_e32 v[44:45], 0
	v_mov_b64_e32 v[46:47], 0
	v_mov_b64_e32 v[56:57], 0
	v_mov_b64_e32 v[58:59], 0
	v_mov_b64_e32 v[60:61], 0
	v_mov_b64_e32 v[62:63], 0
	v_mov_b64_e32 v[64:65], 0
	v_mov_b64_e32 v[66:67], 0
	v_mov_b64_e32 v[68:69], 0
	v_mov_b64_e32 v[70:71], 0
	v_mov_b64_e32 v[80:81], 0
	v_mov_b64_e32 v[82:83], 0
	v_mov_b64_e32 v[84:85], 0
	v_mov_b64_e32 v[86:87], 0
	v_mov_b64_e32 v[96:97], 0
	v_mov_b64_e32 v[98:99], 0
	v_mov_b64_e32 v[100:101], 0
	v_mov_b64_e32 v[102:103], 0
	v_mov_b64_e32 v[112:113], 0
	v_mov_b64_e32 v[114:115], 0
	v_mov_b64_e32 v[116:117], 0
	v_mov_b64_e32 v[118:119], 0
	v_mov_b64_e32 v[72:73], 0
	v_mov_b64_e32 v[74:75], 0
	v_mov_b64_e32 v[76:77], 0
	v_mov_b64_e32 v[78:79], 0
	v_mov_b64_e32 v[88:89], 0
	v_mov_b64_e32 v[90:91], 0
	v_mov_b64_e32 v[92:93], 0
	v_mov_b64_e32 v[94:95], 0
	v_mov_b64_e32 v[104:105], 0
	v_mov_b64_e32 v[106:107], 0
	v_mov_b64_e32 v[108:109], 0
	v_mov_b64_e32 v[110:111], 0
	v_mov_b64_e32 v[120:121], 0
	v_mov_b64_e32 v[122:123], 0
	v_mov_b64_e32 v[124:125], 0
	v_mov_b64_e32 v[126:127], 0

.LBB0_616:
	s_add_u32 s1, s38, 0x100
	v_mov_b32_e32 v0, 0
	s_addc_u32 s51, s39, 0
	s_mov_b32 s52, -2
	s_waitcnt lgkmcnt(0)
	v_mov_b32_e32 v1, v0
	v_mov_b64_e32 v[2:3], 0
	v_mov_b64_e32 v[4:5], 0
	v_mov_b64_e32 v[6:7], 0
	v_mov_b64_e32 v[16:17], 0
	v_mov_b64_e32 v[18:19], 0
	v_mov_b64_e32 v[20:21], 0
	v_mov_b64_e32 v[22:23], 0
	v_mov_b64_e32 v[64:65], 0
	v_mov_b64_e32 v[66:67], 0
	v_mov_b64_e32 v[68:69], 0
	v_mov_b64_e32 v[70:71], 0
	v_mov_b64_e32 v[80:81], 0
	v_mov_b64_e32 v[82:83], 0
	v_mov_b64_e32 v[84:85], 0
	v_mov_b64_e32 v[86:87], 0
	v_mov_b64_e32 v[8:9], 0
	v_mov_b64_e32 v[10:11], 0
	v_mov_b64_e32 v[12:13], 0
	v_mov_b64_e32 v[14:15], 0
	v_mov_b64_e32 v[24:25], 0
	v_mov_b64_e32 v[26:27], 0
	v_mov_b64_e32 v[28:29], 0
	v_mov_b64_e32 v[30:31], 0
	v_mov_b64_e32 v[72:73], 0
	v_mov_b64_e32 v[74:75], 0
	v_mov_b64_e32 v[76:77], 0
	v_mov_b64_e32 v[78:79], 0
	v_mov_b64_e32 v[88:89], 0
	v_mov_b64_e32 v[90:91], 0
	v_mov_b64_e32 v[92:93], 0
	v_mov_b64_e32 v[94:95], 0
	v_mov_b64_e32 v[96:97], 0
	v_mov_b64_e32 v[98:99], 0
	v_mov_b64_e32 v[100:101], 0
	v_mov_b64_e32 v[102:103], 0
	v_mov_b64_e32 v[112:113], 0
	v_mov_b64_e32 v[114:115], 0
	v_mov_b64_e32 v[116:117], 0
	v_mov_b64_e32 v[118:119], 0
	v_mov_b64_e32 v[128:129], 0
	v_mov_b64_e32 v[130:131], 0
	v_mov_b64_e32 v[132:133], 0
	v_mov_b64_e32 v[134:135], 0
	v_mov_b64_e32 v[144:145], 0
	v_mov_b64_e32 v[146:147], 0
	v_mov_b64_e32 v[148:149], 0
	v_mov_b64_e32 v[150:151], 0
	v_mov_b64_e32 v[104:105], 0
	v_mov_b64_e32 v[106:107], 0
	v_mov_b64_e32 v[108:109], 0
	v_mov_b64_e32 v[110:111], 0
	v_mov_b64_e32 v[120:121], 0
	v_mov_b64_e32 v[122:123], 0
	v_mov_b64_e32 v[124:125], 0
	v_mov_b64_e32 v[126:127], 0
	v_mov_b64_e32 v[136:137], 0
	v_mov_b64_e32 v[138:139], 0
	v_mov_b64_e32 v[140:141], 0
	v_mov_b64_e32 v[142:143], 0
	v_mov_b64_e32 v[152:153], 0
	v_mov_b64_e32 v[154:155], 0
	v_mov_b64_e32 v[156:157], 0
	v_mov_b64_e32 v[158:159], 0

.LBB0_703:
	s_ashr_i32 s57, s56, 31
	s_lshl_b64 s[14:15], s[56:57], 19
	v_readlane_b32 s58, v254, 36
	v_readlane_b32 s59, v254, 37
	s_add_u32 s58, s58, s14
	s_addc_u32 s59, s59, s15
	s_and_b64 s[14:15], s[8:9], exec
	s_cselect_b32 s3, s59, s5
	s_cselect_b32 s11, s58, s4
	s_ashr_i32 s55, s54, 31
	s_lshl_b64 s[14:15], s[54:55], 19
	s_add_u32 s60, s20, s14
	s_addc_u32 s61, s21, s15
	s_and_b64 s[14:15], s[8:9], exec
	s_cselect_b32 s14, s61, s7
	s_cselect_b32 s15, s60, s6
	s_add_u32 s4, s4, 0x40080
	s_addc_u32 s5, s5, 0
	s_add_u32 s28, s6, 0x100
	v_mov_b32_e32 v0, 0
	s_addc_u32 s55, s7, 0
	s_mov_b32 s57, -2
	v_mov_b32_e32 v1, v0
	v_mov_b64_e32 v[2:3], 0
	v_mov_b64_e32 v[4:5], 0
	v_mov_b64_e32 v[6:7], 0
	v_mov_b64_e32 v[8:9], 0
	v_mov_b64_e32 v[10:11], 0
	v_mov_b64_e32 v[12:13], 0
	v_mov_b64_e32 v[14:15], 0
	v_mov_b64_e32 v[24:25], 0
	v_mov_b64_e32 v[26:27], 0
	v_mov_b64_e32 v[28:29], 0
	v_mov_b64_e32 v[30:31], 0
	v_mov_b64_e32 v[36:37], 0
	v_mov_b64_e32 v[38:39], 0
	v_mov_b64_e32 v[44:45], 0
	v_mov_b64_e32 v[46:47], 0
	v_mov_b32_e32 v16, v0
	s_waitcnt lgkmcnt(0)
	v_mov_b32_e32 v17, v0
	v_mov_b64_e32 v[18:19], 0
	v_mov_b64_e32 v[20:21], 0
	v_mov_b64_e32 v[22:23], 0
	v_mov_b64_e32 v[32:33], 0
	v_mov_b64_e32 v[34:35], 0
	v_mov_b64_e32 v[40:41], 0
	v_mov_b64_e32 v[42:43], 0
	v_mov_b64_e32 v[48:49], 0
	v_mov_b64_e32 v[50:51], 0
	v_mov_b64_e32 v[52:53], 0
	v_mov_b64_e32 v[54:55], 0
	v_mov_b64_e32 v[56:57], 0
	v_mov_b64_e32 v[58:59], 0
	v_mov_b64_e32 v[60:61], 0
	v_mov_b64_e32 v[62:63], 0
	v_mov_b64_e32 v[64:65], 0
	v_mov_b64_e32 v[66:67], 0
	v_mov_b64_e32 v[68:69], 0
	v_mov_b64_e32 v[70:71], 0
	v_mov_b64_e32 v[72:73], 0
	v_mov_b64_e32 v[74:75], 0
	v_mov_b64_e32 v[76:77], 0
	v_mov_b64_e32 v[78:79], 0
	v_mov_b64_e32 v[84:85], 0
	v_mov_b64_e32 v[86:87], 0
	v_mov_b64_e32 v[92:93], 0
	v_mov_b64_e32 v[94:95], 0
	v_mov_b64_e32 v[96:97], 0
	v_mov_b64_e32 v[98:99], 0
	v_mov_b64_e32 v[104:105], 0
	v_mov_b64_e32 v[106:107], 0
	v_mov_b64_e32 v[80:81], 0
	v_mov_b64_e32 v[82:83], 0
	v_mov_b64_e32 v[88:89], 0
	v_mov_b64_e32 v[90:91], 0
	v_mov_b64_e32 v[100:101], 0
	v_mov_b64_e32 v[102:103], 0
	v_mov_b64_e32 v[108:109], 0
	v_mov_b64_e32 v[110:111], 0
	v_mov_b64_e32 v[112:113], 0
	v_mov_b64_e32 v[114:115], 0
	v_mov_b64_e32 v[116:117], 0
	v_mov_b64_e32 v[118:119], 0
	v_mov_b64_e32 v[120:121], 0
	v_mov_b64_e32 v[122:123], 0
	v_mov_b64_e32 v[124:125], 0
	v_mov_b64_e32 v[126:127], 0

.LBB0_861:
	s_add_u32 s56, s42, 0x100
	v_mov_b32_e32 v0, 0
	s_addc_u32 s57, s43, 0
	s_mov_b32 s58, -2
	v_mov_b32_e32 v1, v0
	v_mov_b64_e32 v[2:3], 0
	v_mov_b64_e32 v[4:5], 0
	v_mov_b64_e32 v[6:7], 0
	v_mov_b64_e32 v[16:17], 0
	v_mov_b64_e32 v[18:19], 0
	v_mov_b64_e32 v[20:21], 0
	v_mov_b64_e32 v[22:23], 0
	v_mov_b64_e32 v[32:33], 0
	v_mov_b64_e32 v[34:35], 0
	v_mov_b64_e32 v[36:37], 0
	v_mov_b64_e32 v[38:39], 0
	v_mov_b64_e32 v[48:49], 0
	v_mov_b64_e32 v[50:51], 0
	v_mov_b64_e32 v[52:53], 0
	v_mov_b64_e32 v[54:55], 0
	v_mov_b64_e32 v[8:9], 0
	v_mov_b64_e32 v[10:11], 0
	v_mov_b64_e32 v[12:13], 0
	v_mov_b64_e32 v[14:15], 0
	v_mov_b64_e32 v[24:25], 0
	v_mov_b64_e32 v[26:27], 0
	v_mov_b64_e32 v[28:29], 0
	v_mov_b64_e32 v[30:31], 0
	v_mov_b64_e32 v[40:41], 0
	v_mov_b64_e32 v[42:43], 0
	v_mov_b64_e32 v[44:45], 0
	v_mov_b64_e32 v[46:47], 0
	v_mov_b64_e32 v[56:57], 0
	v_mov_b64_e32 v[58:59], 0
	v_mov_b64_e32 v[60:61], 0
	v_mov_b64_e32 v[62:63], 0
	v_mov_b64_e32 v[64:65], 0
	v_mov_b64_e32 v[66:67], 0
	v_mov_b64_e32 v[68:69], 0
	v_mov_b64_e32 v[70:71], 0
	v_mov_b64_e32 v[80:81], 0
	v_mov_b64_e32 v[82:83], 0
	v_mov_b64_e32 v[84:85], 0
	v_mov_b64_e32 v[86:87], 0
	v_mov_b64_e32 v[96:97], 0
	v_mov_b64_e32 v[98:99], 0
	v_mov_b64_e32 v[100:101], 0
	v_mov_b64_e32 v[102:103], 0
	v_mov_b64_e32 v[112:113], 0
	v_mov_b64_e32 v[114:115], 0
	v_mov_b64_e32 v[116:117], 0
	v_mov_b64_e32 v[118:119], 0
	v_mov_b64_e32 v[72:73], 0
	v_mov_b64_e32 v[74:75], 0
	v_mov_b64_e32 v[76:77], 0
	v_mov_b64_e32 v[78:79], 0
	v_mov_b64_e32 v[88:89], 0
	v_mov_b64_e32 v[90:91], 0
	v_mov_b64_e32 v[92:93], 0
	v_mov_b64_e32 v[94:95], 0
	v_mov_b64_e32 v[104:105], 0
	v_mov_b64_e32 v[106:107], 0
	v_mov_b64_e32 v[108:109], 0
	v_mov_b64_e32 v[110:111], 0
	v_mov_b64_e32 v[120:121], 0
	v_mov_b64_e32 v[122:123], 0
	v_mov_b64_e32 v[124:125], 0
	v_mov_b64_e32 v[126:127], 0

.LBB0_893:
	s_ashr_i32 s19, s18, 31
	s_lshl_b64 s[20:21], s[18:19], 17
	s_add_u32 s20, s12, s20
	s_addc_u32 s21, s13, s21
	s_and_b64 s[22:23], s[4:5], exec
	s_cselect_b32 s19, s21, s35
	s_cselect_b32 s53, s20, s34
	s_ashr_i32 s9, s8, 31
	s_lshl_b64 s[22:23], s[8:9], 17
	s_add_u32 s22, s16, s22
	s_addc_u32 s23, s17, s23
	s_and_b64 s[36:37], s[4:5], exec
	v_mov_b32_e32 v0, 0
	s_cselect_b32 s9, s23, s31
	s_cselect_b32 s54, s22, s30
	s_mov_b64 s[40:41], 0
	s_mov_b64 s[36:37], -1
	s_mov_b64 s[38:39], 0
	v_mov_b32_e32 v1, v0
	v_mov_b64_e32 v[2:3], 0
	v_mov_b64_e32 v[4:5], 0
	v_mov_b64_e32 v[6:7], 0
	v_mov_b64_e32 v[16:17], 0
	v_mov_b64_e32 v[18:19], 0
	v_mov_b64_e32 v[20:21], 0
	v_mov_b64_e32 v[22:23], 0
	v_mov_b64_e32 v[32:33], 0
	v_mov_b64_e32 v[34:35], 0
	v_mov_b64_e32 v[36:37], 0
	v_mov_b64_e32 v[38:39], 0
	v_mov_b64_e32 v[48:49], 0
	v_mov_b64_e32 v[50:51], 0
	v_mov_b64_e32 v[52:53], 0
	v_mov_b64_e32 v[54:55], 0
	v_mov_b64_e32 v[8:9], 0
	v_mov_b64_e32 v[10:11], 0
	v_mov_b64_e32 v[12:13], 0
	v_mov_b64_e32 v[14:15], 0
	v_mov_b64_e32 v[24:25], 0
	v_mov_b64_e32 v[26:27], 0
	v_mov_b64_e32 v[28:29], 0
	v_mov_b64_e32 v[30:31], 0
	v_mov_b64_e32 v[40:41], 0
	v_mov_b64_e32 v[42:43], 0
	v_mov_b64_e32 v[44:45], 0
	v_mov_b64_e32 v[46:47], 0
	v_mov_b64_e32 v[56:57], 0
	v_mov_b64_e32 v[58:59], 0
	v_mov_b64_e32 v[60:61], 0
	v_mov_b64_e32 v[62:63], 0
	v_mov_b64_e32 v[64:65], 0
	v_mov_b64_e32 v[66:67], 0
	v_mov_b64_e32 v[68:69], 0
	v_mov_b64_e32 v[70:71], 0
	v_mov_b64_e32 v[80:81], 0
	v_mov_b64_e32 v[82:83], 0
	v_mov_b64_e32 v[84:85], 0
	v_mov_b64_e32 v[86:87], 0
	v_mov_b64_e32 v[96:97], 0
	v_mov_b64_e32 v[98:99], 0
	v_mov_b64_e32 v[100:101], 0
	v_mov_b64_e32 v[102:103], 0
	v_mov_b64_e32 v[112:113], 0
	v_mov_b64_e32 v[114:115], 0
	v_mov_b64_e32 v[116:117], 0
	v_mov_b64_e32 v[118:119], 0
	v_mov_b64_e32 v[72:73], 0
	v_mov_b64_e32 v[74:75], 0
	v_mov_b64_e32 v[76:77], 0
	v_mov_b64_e32 v[78:79], 0
	v_mov_b64_e32 v[88:89], 0
	v_mov_b64_e32 v[90:91], 0
	v_mov_b64_e32 v[92:93], 0
	v_mov_b64_e32 v[94:95], 0
	v_mov_b64_e32 v[104:105], 0
	v_mov_b64_e32 v[106:107], 0
	v_mov_b64_e32 v[108:109], 0
	v_mov_b64_e32 v[110:111], 0
	v_mov_b64_e32 v[120:121], 0
	v_mov_b64_e32 v[122:123], 0
	v_mov_b64_e32 v[124:125], 0
	v_mov_b64_e32 v[126:127], 0

.LBB0_1242:
	s_ashr_i32 s13, s12, 31
	s_lshl_b64 s[14:15], s[12:13], 19
	s_add_u32 s14, s0, s14
	s_addc_u32 s15, s1, s15
	s_and_b64 s[16:17], s[4:5], exec
	s_cselect_b32 s13, s15, s19
	s_cselect_b32 s40, s14, s18
	s_ashr_i32 s11, s10, 31
	s_lshl_b64 s[16:17], s[10:11], 19
	s_add_u32 s16, s66, s16
	s_addc_u32 s17, s67, s17
	s_and_b64 s[22:23], s[4:5], exec
	s_cselect_b32 s11, s17, s21
	s_cselect_b32 s41, s16, s20
	s_add_u32 s18, s18, 0x40080
	s_addc_u32 s19, s19, 0
	s_add_u32 s42, s20, 0x100
	v_mov_b32_e32 v0, 0
	s_addc_u32 s43, s21, 0
	s_mov_b32 s44, -2
	v_mov_b32_e32 v1, v0
	v_mov_b64_e32 v[2:3], 0
	v_mov_b64_e32 v[4:5], 0
	v_mov_b64_e32 v[6:7], 0
	v_mov_b64_e32 v[8:9], 0
	v_mov_b64_e32 v[10:11], 0
	v_mov_b64_e32 v[12:13], 0
	v_mov_b64_e32 v[14:15], 0
	v_mov_b64_e32 v[24:25], 0
	v_mov_b64_e32 v[26:27], 0
	v_mov_b64_e32 v[28:29], 0
	v_mov_b64_e32 v[30:31], 0
	v_mov_b64_e32 v[36:37], 0
	v_mov_b64_e32 v[38:39], 0
	v_mov_b64_e32 v[44:45], 0
	v_mov_b64_e32 v[46:47], 0
	v_mov_b64_e32 v[16:17], 0
	v_mov_b64_e32 v[18:19], 0
	v_mov_b64_e32 v[20:21], 0
	v_mov_b64_e32 v[22:23], 0
	v_mov_b64_e32 v[32:33], 0
	v_mov_b64_e32 v[34:35], 0
	v_mov_b64_e32 v[40:41], 0
	v_mov_b64_e32 v[42:43], 0
	v_mov_b64_e32 v[48:49], 0
	v_mov_b64_e32 v[50:51], 0
	v_mov_b64_e32 v[52:53], 0
	v_mov_b64_e32 v[54:55], 0
	v_mov_b64_e32 v[56:57], 0
	v_mov_b64_e32 v[58:59], 0
	v_mov_b64_e32 v[60:61], 0
	v_mov_b64_e32 v[62:63], 0
	v_mov_b64_e32 v[64:65], 0
	v_mov_b64_e32 v[66:67], 0
	v_mov_b64_e32 v[68:69], 0
	v_mov_b64_e32 v[70:71], 0
	v_mov_b64_e32 v[72:73], 0
	v_mov_b64_e32 v[74:75], 0
	v_mov_b64_e32 v[76:77], 0
	v_mov_b64_e32 v[78:79], 0
	v_mov_b64_e32 v[84:85], 0
	v_mov_b64_e32 v[86:87], 0
	v_mov_b64_e32 v[92:93], 0
	v_mov_b64_e32 v[94:95], 0
	v_mov_b64_e32 v[96:97], 0
	v_mov_b64_e32 v[98:99], 0
	v_mov_b64_e32 v[104:105], 0
	v_mov_b64_e32 v[106:107], 0
	v_mov_b64_e32 v[80:81], 0
	v_mov_b64_e32 v[82:83], 0
	v_mov_b64_e32 v[88:89], 0
	v_mov_b64_e32 v[90:91], 0
	v_mov_b64_e32 v[100:101], 0
	v_mov_b64_e32 v[102:103], 0
	v_mov_b64_e32 v[108:109], 0
	v_mov_b64_e32 v[110:111], 0
	v_mov_b64_e32 v[112:113], 0
	v_mov_b64_e32 v[114:115], 0
	v_mov_b64_e32 v[116:117], 0
	v_mov_b64_e32 v[118:119], 0
	v_mov_b64_e32 v[120:121], 0
	v_mov_b64_e32 v[122:123], 0
	v_mov_b64_e32 v[124:125], 0
	v_mov_b64_e32 v[126:127], 0

.LBB0_1324:
	s_add_u32 s21, s24, 0x100
	v_mov_b32_e32 v0, 0
	s_addc_u32 s46, s25, 0
	s_mov_b32 s47, -2
	v_mov_b32_e32 v1, v0
	v_mov_b64_e32 v[2:3], 0
	v_mov_b64_e32 v[4:5], 0
	v_mov_b64_e32 v[6:7], 0
	v_mov_b64_e32 v[16:17], 0
	v_mov_b64_e32 v[18:19], 0
	v_mov_b64_e32 v[20:21], 0
	v_mov_b64_e32 v[22:23], 0
	v_mov_b64_e32 v[32:33], 0
	v_mov_b64_e32 v[34:35], 0
	v_mov_b64_e32 v[36:37], 0
	v_mov_b64_e32 v[38:39], 0
	v_mov_b64_e32 v[48:49], 0
	v_mov_b64_e32 v[50:51], 0
	v_mov_b64_e32 v[52:53], 0
	v_mov_b64_e32 v[54:55], 0
	v_mov_b64_e32 v[8:9], 0
	v_mov_b64_e32 v[10:11], 0
	v_mov_b64_e32 v[12:13], 0
	v_mov_b64_e32 v[14:15], 0
	v_mov_b64_e32 v[24:25], 0
	v_mov_b64_e32 v[26:27], 0
	v_mov_b64_e32 v[28:29], 0
	v_mov_b64_e32 v[30:31], 0
	v_mov_b64_e32 v[40:41], 0
	v_mov_b64_e32 v[42:43], 0
	v_mov_b64_e32 v[44:45], 0
	v_mov_b64_e32 v[46:47], 0
	v_mov_b64_e32 v[56:57], 0
	v_mov_b64_e32 v[58:59], 0
	v_mov_b64_e32 v[60:61], 0
	v_mov_b64_e32 v[62:63], 0
	v_mov_b64_e32 v[64:65], 0
	v_mov_b64_e32 v[66:67], 0
	v_mov_b64_e32 v[68:69], 0
	v_mov_b64_e32 v[70:71], 0
	v_mov_b64_e32 v[80:81], 0
	v_mov_b64_e32 v[82:83], 0
	v_mov_b64_e32 v[84:85], 0
	v_mov_b64_e32 v[86:87], 0
	v_mov_b64_e32 v[96:97], 0
	v_mov_b64_e32 v[98:99], 0
	v_mov_b64_e32 v[100:101], 0
	v_mov_b64_e32 v[102:103], 0
	v_mov_b64_e32 v[112:113], 0
	v_mov_b64_e32 v[114:115], 0
	v_mov_b64_e32 v[116:117], 0
	v_mov_b64_e32 v[118:119], 0
	v_mov_b64_e32 v[72:73], 0
	v_mov_b64_e32 v[74:75], 0
	v_mov_b64_e32 v[76:77], 0
	v_mov_b64_e32 v[78:79], 0
	v_mov_b64_e32 v[88:89], 0
	v_mov_b64_e32 v[90:91], 0
	v_mov_b64_e32 v[92:93], 0
	v_mov_b64_e32 v[94:95], 0
	v_mov_b64_e32 v[104:105], 0
	v_mov_b64_e32 v[106:107], 0
	v_mov_b64_e32 v[108:109], 0
	v_mov_b64_e32 v[110:111], 0
	v_mov_b64_e32 v[124:125], 0
	v_mov_b64_e32 v[126:127], 0
	v_mov_b64_e32 v[132:133], 0
	v_mov_b64_e32 v[134:135], 0
